# attention steady-state step: the 32 scalar f32 row-sum adds become 16 packed f32 adds (two partial sums combined at the end)
# baseline (speedup 1.0000x reference)
.LBB0_404:
	v_add_u32_e32 v0, s24, v236
	ds_read_b64_tr_b16 v[192:193], v0 offset:24576
	ds_read_b64_tr_b16 v[194:195], v0 offset:25088
	v_pk_add_f32 v[2:3], v[80:81], v[82:83]
	v_pk_add_f32 v[2:3], v[2:3], v[84:85]
	v_cvt_pk_bf16_f32 v156, v80, v81
	v_cvt_pk_bf16_f32 v157, v82, v83
	s_waitcnt lgkmcnt(9)
	v_mfma_f32_32x32x16_bf16 v[96:111], v[188:191], v[144:147], v[48:63]
	ds_read_b64_tr_b16 v[188:189], v0 offset:28672
	ds_read_b64_tr_b16 v[190:191], v0 offset:29184
	v_pk_add_f32 v[2:3], v[2:3], v[86:87]
	v_pk_add_f32 v[2:3], v[2:3], v[88:89]
	v_cvt_pk_bf16_f32 v158, v84, v85
	v_cvt_pk_bf16_f32 v159, v86, v87
	s_waitcnt lgkmcnt(10)
	v_mfma_f32_32x32x16_bf16 v[112:127], v[184:187], v[144:147], v[48:63]
	ds_read_b64_tr_b16 v[184:185], v0 offset:25600
	ds_read_b64_tr_b16 v[186:187], v0 offset:26112
	v_pk_add_f32 v[2:3], v[2:3], v[90:91]
	v_pk_add_f32 v[2:3], v[2:3], v[92:93]
	v_cvt_pk_bf16_f32 v152, v88, v89
	v_cvt_pk_bf16_f32 v153, v90, v91
	s_waitcnt lgkmcnt(11)
	v_mfma_f32_32x32x16_bf16 v[96:111], v[180:183], v[136:139], v[96:111]
	ds_read_b64_tr_b16 v[180:181], v0 offset:29696
	ds_read_b64_tr_b16 v[182:183], v0 offset:30208
	v_pk_add_f32 v[2:3], v[2:3], v[94:95]
	v_pk_add_f32 v[2:3], v[2:3], v[64:65]
	v_cvt_pk_bf16_f32 v154, v92, v93
	v_cvt_pk_bf16_f32 v155, v94, v95
	s_waitcnt lgkmcnt(12)
	v_mfma_f32_32x32x16_bf16 v[112:127], v[176:179], v[136:139], v[112:127]
	ds_read_b64_tr_b16 v[176:177], v0 offset:26624
	ds_read_b64_tr_b16 v[178:179], v0 offset:27136
	v_pk_add_f32 v[2:3], v[2:3], v[66:67]
	v_pk_add_f32 v[2:3], v[2:3], v[68:69]
	v_cvt_pk_bf16_f32 v148, v64, v65
	v_cvt_pk_bf16_f32 v149, v66, v67
	s_waitcnt lgkmcnt(13)
	v_mfma_f32_32x32x16_bf16 v[96:111], v[172:175], v[132:135], v[96:111]
	ds_read_b64_tr_b16 v[10:11], v0 offset:30720
	ds_read_b64_tr_b16 v[12:13], v0 offset:31232
	v_pk_add_f32 v[2:3], v[2:3], v[70:71]
	v_pk_add_f32 v[2:3], v[2:3], v[72:73]
	v_cvt_pk_bf16_f32 v150, v68, v69
	v_cvt_pk_bf16_f32 v151, v70, v71
	s_waitcnt lgkmcnt(14)
	v_mfma_f32_32x32x16_bf16 v[112:127], v[168:171], v[132:135], v[112:127]
	ds_read_b64_tr_b16 v[6:7], v0 offset:27648
	ds_read_b64_tr_b16 v[8:9], v0 offset:28160
	v_pk_add_f32 v[2:3], v[2:3], v[74:75]
	v_pk_add_f32 v[14:15], v[2:3], v[76:77]
	v_cvt_pk_bf16_f32 v140, v72, v73
	v_cvt_pk_bf16_f32 v141, v74, v75
	s_waitcnt lgkmcnt(14)
	v_mfma_f32_32x32x16_bf16 v[96:111], v[164:167], v[128:131], v[96:111]
	ds_read_b64_tr_b16 v[2:3], v0 offset:31744
	ds_read_b64_tr_b16 v[4:5], v0 offset:32256
	v_pk_add_f32 v[14:15], v[14:15], v[78:79]
	v_add_f32_e32 v0, v14, v15
	v_cvt_pk_bf16_f32 v142, v76, v77
	v_cvt_pk_bf16_f32 v143, v78, v79
	v_mfma_f32_32x32x16_bf16 v[112:127], v[160:163], v[128:131], v[112:127]
	v_lshl_add_u64 v[14:15], v[206:207], 0, s[38:39]
	s_add_i32 s24, s52, s85
	s_mov_b32 s25, m0
	s_mov_b32 m0, s24
	s_nop 0
	global_load_lds_dwordx4 v[14:15], off
	s_mov_b32 m0, s25
	v_lshl_add_u64 v[14:15], v[204:205], 0, s[38:39]
	s_add_i32 s24, s50, s86
	s_mov_b32 s25, m0
	s_mov_b32 m0, s24
	s_nop 0
	global_load_lds_dwordx4 v[14:15], off
	s_mov_b32 m0, s25
	v_mov_b32_e32 v14, v229
	s_nop 0
	v_lshl_add_u32 v80, v14, 4, s51
	ds_read_b128 v[160:163], v80
	ds_read_b128 v[164:167], v80 offset:128
	ds_read_b128 v[168:171], v80 offset:32
	ds_read_b128 v[172:175], v80 offset:160
	ds_read_b128 v[196:199], v80 offset:64
	ds_read_b128 v[240:243], v80 offset:192
	ds_read_b128 v[244:247], v80 offset:96
	ds_read_b128 v[252:255], v80 offset:224
	s_waitcnt lgkmcnt(7)
	v_pk_add_f32 v[64:65], v[96:97], v[160:161]
	v_pk_add_f32 v[82:83], v[98:99], v[162:163]
	s_waitcnt lgkmcnt(6)
	v_pk_add_f32 v[14:15], v[112:113], v[164:165]
	v_pk_add_f32 v[66:67], v[114:115], v[166:167]
	s_waitcnt lgkmcnt(5)
	v_pk_add_f32 v[84:85], v[100:101], v[168:169]
	v_pk_add_f32 v[86:87], v[102:103], v[170:171]
	s_waitcnt lgkmcnt(4)
	v_pk_add_f32 v[68:69], v[116:117], v[172:173]
	v_pk_add_f32 v[70:71], v[118:119], v[174:175]
	s_waitcnt lgkmcnt(3)
	v_pk_add_f32 v[88:89], v[104:105], v[196:197]
	v_pk_add_f32 v[90:91], v[106:107], v[198:199]
	s_waitcnt lgkmcnt(2)
	v_pk_add_f32 v[72:73], v[120:121], v[240:241]
	v_pk_add_f32 v[74:75], v[122:123], v[242:243]
	s_waitcnt lgkmcnt(1)
	v_pk_add_f32 v[92:93], v[108:109], v[244:245]
	v_pk_add_f32 v[94:95], v[110:111], v[246:247]
	s_waitcnt lgkmcnt(0)
	v_pk_add_f32 v[76:77], v[124:125], v[252:253]
	v_pk_add_f32 v[78:79], v[126:127], v[254:255]
	v_max_f32_e32 v80, v64, v65
	v_max3_f32 v81, v82, v83, v15
	v_max3_f32 v80, v80, v14, v66
	v_max3_f32 v80, v80, v67, v84
	v_max3_f32 v81, v81, v86, v87
	v_max3_f32 v80, v80, v85, v68
	v_max3_f32 v81, v81, v70, v71
	v_max3_f32 v80, v80, v69, v88
	v_max3_f32 v81, v81, v90, v91
	v_max3_f32 v80, v80, v89, v72
	v_max3_f32 v81, v81, v74, v75
	v_max3_f32 v80, v80, v73, v92
	v_max3_f32 v81, v81, v94, v95
	v_max3_f32 v80, v80, v93, v76
	v_max3_f32 v81, v81, v78, v79
	v_add_f32_e32 v209, v238, v0
	v_max3_f32 v0, v80, v77, v81
	v_mov_b32_e32 v80, v0
	s_nop 1
	v_permlane32_swap_b32_e32 v0, v80
	v_max_f32_e32 v80, v80, v80
	v_max_f32_e32 v0, v0, v0
	v_max_f32_e32 v0, v0, v80
	v_cmp_lt_f32_e32 vcc, s92, v0
	s_cmp_lg_u64 vcc, 0
	s_cselect_b64 s[46:47], -1, 0
	s_cbranch_vccnz .LBB0_412

.LBB0_407:
	s_add_i32 s24, s50, 0x2000
	s_cmpk_lg_i32 s50, 0x4000
	s_cselect_b32 s96, s24, 0
	v_add_u32_e32 v4, s52, v236
	ds_read_b64_tr_b16 v[176:177], v4 offset:24576
	ds_read_b64_tr_b16 v[178:179], v4 offset:25088
	v_pk_add_f32 v[2:3], v[80:81], v[82:83]
	v_pk_add_f32 v[2:3], v[2:3], v[84:85]
	v_cvt_pk_bf16_f32 v156, v80, v81
	v_cvt_pk_bf16_f32 v157, v82, v83
	s_waitcnt lgkmcnt(9)
	v_mfma_f32_32x32x16_bf16 v[96:111], v[112:115], v[144:147], v[48:63]
	ds_read_b64_tr_b16 v[172:173], v4 offset:28672
	ds_read_b64_tr_b16 v[174:175], v4 offset:29184
	v_pk_add_f32 v[2:3], v[2:3], v[86:87]
	v_pk_add_f32 v[2:3], v[2:3], v[88:89]
	v_cvt_pk_bf16_f32 v158, v84, v85
	v_cvt_pk_bf16_f32 v159, v86, v87
	s_waitcnt lgkmcnt(10)
	v_mfma_f32_32x32x16_bf16 v[112:127], v[164:167], v[144:147], v[48:63]
	ds_read_b64_tr_b16 v[168:169], v4 offset:25600
	ds_read_b64_tr_b16 v[170:171], v4 offset:26112
	v_pk_add_f32 v[2:3], v[2:3], v[90:91]
	v_pk_add_f32 v[2:3], v[2:3], v[92:93]
	v_cvt_pk_bf16_f32 v152, v88, v89
	v_cvt_pk_bf16_f32 v153, v90, v91
	s_waitcnt lgkmcnt(11)
	v_mfma_f32_32x32x16_bf16 v[96:111], v[196:199], v[136:139], v[96:111]
	ds_read_b64_tr_b16 v[164:165], v4 offset:29696
	ds_read_b64_tr_b16 v[166:167], v4 offset:30208
	v_pk_add_f32 v[2:3], v[2:3], v[94:95]
	v_pk_add_f32 v[2:3], v[2:3], v[64:65]
	v_cvt_pk_bf16_f32 v154, v92, v93
	v_cvt_pk_bf16_f32 v155, v94, v95
	s_waitcnt lgkmcnt(12)
	v_mfma_f32_32x32x16_bf16 v[112:127], v[160:163], v[136:139], v[112:127]
	ds_read_b64_tr_b16 v[160:161], v4 offset:26624
	ds_read_b64_tr_b16 v[162:163], v4 offset:27136
	v_pk_add_f32 v[2:3], v[2:3], v[66:67]
	v_pk_add_f32 v[2:3], v[2:3], v[68:69]
	v_cvt_pk_bf16_f32 v148, v64, v65
	v_cvt_pk_bf16_f32 v149, v66, v67
	s_waitcnt lgkmcnt(13)
	v_mfma_f32_32x32x16_bf16 v[96:111], v[192:195], v[132:135], v[96:111]
	ds_read_b64_tr_b16 v[10:11], v4 offset:30720
	ds_read_b64_tr_b16 v[12:13], v4 offset:31232
	v_pk_add_f32 v[2:3], v[2:3], v[70:71]
	v_pk_add_f32 v[2:3], v[2:3], v[72:73]
	v_cvt_pk_bf16_f32 v150, v68, v69
	v_cvt_pk_bf16_f32 v151, v70, v71
	s_waitcnt lgkmcnt(14)
	v_mfma_f32_32x32x16_bf16 v[112:127], v[184:187], v[132:135], v[112:127]
	ds_read_b64_tr_b16 v[6:7], v4 offset:27648
	ds_read_b64_tr_b16 v[8:9], v4 offset:28160
	v_pk_add_f32 v[2:3], v[2:3], v[74:75]
	v_pk_add_f32 v[14:15], v[2:3], v[76:77]
	v_cvt_pk_bf16_f32 v140, v72, v73
	v_cvt_pk_bf16_f32 v141, v74, v75
	s_waitcnt lgkmcnt(14)
	v_mfma_f32_32x32x16_bf16 v[96:111], v[188:191], v[128:131], v[96:111]
	ds_read_b64_tr_b16 v[2:3], v4 offset:31744
	ds_read_b64_tr_b16 v[4:5], v4 offset:32256
	v_pk_add_f32 v[14:15], v[14:15], v[78:79]
	v_add_f32_e32 v80, v14, v15
	v_cvt_pk_bf16_f32 v142, v76, v77
	v_cvt_pk_bf16_f32 v143, v78, v79
	v_mfma_f32_32x32x16_bf16 v[112:127], v[180:183], v[128:131], v[112:127]
	s_add_i32 s24, s50, s85
	s_mov_b32 s25, m0
	s_mov_b32 m0, s24
	s_nop 0
	global_load_lds_dwordx4 v[206:207], off
	s_mov_b32 m0, s25
	v_mov_b32_e32 v14, v229
	s_add_i32 s24, s96, s86
	s_mov_b32 s25, m0
	s_mov_b32 m0, s24
	s_nop 0
	global_load_lds_dwordx4 v[204:205], off
	s_mov_b32 m0, s25
	s_nop 0
	v_lshl_add_u32 v81, v14, 4, s51
	ds_read_b128 v[180:183], v81 offset:256
	ds_read_b128 v[184:187], v81 offset:384
	ds_read_b128 v[188:191], v81 offset:288
	ds_read_b128 v[192:195], v81 offset:416
	ds_read_b128 v[196:199], v81 offset:320
	ds_read_b128 v[240:243], v81 offset:448
	ds_read_b128 v[244:247], v81 offset:352
	ds_read_b128 v[252:255], v81 offset:480
	s_waitcnt lgkmcnt(7)
	v_pk_add_f32 v[64:65], v[96:97], v[180:181]
	v_pk_add_f32 v[82:83], v[98:99], v[182:183]
	s_waitcnt lgkmcnt(6)
	v_pk_add_f32 v[14:15], v[112:113], v[184:185]
	v_pk_add_f32 v[66:67], v[114:115], v[186:187]
	s_waitcnt lgkmcnt(5)
	v_pk_add_f32 v[84:85], v[100:101], v[188:189]
	v_pk_add_f32 v[86:87], v[102:103], v[190:191]
	s_waitcnt lgkmcnt(4)
	v_pk_add_f32 v[68:69], v[116:117], v[192:193]
	v_pk_add_f32 v[70:71], v[118:119], v[194:195]
	s_waitcnt lgkmcnt(3)
	v_pk_add_f32 v[88:89], v[104:105], v[196:197]
	v_pk_add_f32 v[90:91], v[106:107], v[198:199]
	s_waitcnt lgkmcnt(2)
	v_pk_add_f32 v[72:73], v[120:121], v[240:241]
	v_pk_add_f32 v[74:75], v[122:123], v[242:243]
	s_waitcnt lgkmcnt(1)
	v_pk_add_f32 v[92:93], v[108:109], v[244:245]
	v_pk_add_f32 v[94:95], v[110:111], v[246:247]
	s_waitcnt lgkmcnt(0)
	v_pk_add_f32 v[76:77], v[124:125], v[252:253]
	v_pk_add_f32 v[78:79], v[126:127], v[254:255]
	v_max_f32_e32 v81, v64, v65
	v_max3_f32 v96, v82, v83, v15
	v_max3_f32 v81, v81, v14, v66
	v_max3_f32 v81, v81, v67, v84
	v_max3_f32 v96, v96, v86, v87
	v_max3_f32 v81, v81, v85, v68
	v_max3_f32 v96, v96, v70, v71
	v_max3_f32 v81, v81, v69, v88
	v_max3_f32 v96, v96, v90, v91
	v_max3_f32 v81, v81, v89, v72
	v_max3_f32 v96, v96, v74, v75
	v_max3_f32 v81, v81, v73, v92
	v_max3_f32 v96, v96, v94, v95
	v_max3_f32 v81, v81, v93, v76
	v_max3_f32 v96, v96, v78, v79
	v_add_f32_e32 v238, v209, v80
	v_max3_f32 v80, v81, v77, v96
	v_mov_b32_e32 v81, v80
	s_nop 1
	v_permlane32_swap_b32_e32 v80, v81
	v_max_f32_e32 v81, v81, v81
	v_max_f32_e32 v80, v80, v80
	v_max_f32_e32 v80, v80, v81
	v_cmp_lt_f32_e32 vcc, s92, v80
	s_cmp_lg_u64 vcc, 0
	s_cselect_b64 s[46:47], -1, 0
	s_cbranch_vccnz .LBB0_415
